# fp8 expert-table conversion moved from the start of phase 10 into the phase 9 GEMM tile epilogues (one row of each table per wave per tile, loads issued at the top of the epilogue, converted after the
# speedup vs baseline: 1.0204x; 1.0043x over previous
; DEVI unsigned pack2(float a, float b) { return (unsigned)f2bf(a) | ((unsigned)f2bf(b) << 16); }
; DEVI void conv_fp8_rows(const float* __restrict__ src, unsigned char* __restrict__ dst, float* __restrict__ inv_scale,
;                         int rows, int gw, int nw, int lane) {
;   for (int r0 = gw; r0 < rows; r0 += 2 * nw) {
;     const int r1 = r0 + nw;
;     const bool has1 = r1 < rows;
;     const float4* p0 = (const float4*)(src + (size_t)r0 * 1024) + lane * 4;
;     const float4* p1 = (const float4*)(src + (size_t)(has1 ? r1 : r0) * 1024) + lane * 4;
;     float4 v[2][4];
; #pragma unroll
;     for (int i = 0; i < 4; ++i) { v[0][i] = p0[i]; v[1][i] = p1[i]; }
; DEVI void phase_scaled(const Params& p, unsigned char* smem, const u16* A, const u16* Wt, int ntn, const float* ssq, u16* outp, int ldo) {
;     ...
; #pragma unroll
;     for (int mi = 0; mi < 4; ++mi) {
;       const int m = m0 + wm * 64 + 16 * mi + col;
;       const float rstd = rsqrtf(ssq[m] * (1.f / D) + 1e-6f);
; #pragma unroll
;       for (int ni = 0; ni < 4; ++ni) {
;         const int n = n0 + wn * 64 + 16 * ni + 4 * quad;
;         const f32x4 v = acc[ni][mi];
;         uint2 pk; pk.x = pack2(v[0] * rstd, v[1] * rstd); pk.y = pack2(v[2] * rstd, v[3] * rstd);
;         *(uint2*)(outp + (size_t)m * ldo + n) = pk;
;       }
.LBB0_1158:
	v_and_b32_e32 v200, 63, v210
	v_lshrrev_b32_e32 v201, 6, v210
	v_and_b32_e32 v202, 15, v200
	v_lshrrev_b32_e32 v203, 4, v200
	v_lshlrev_b32_e32 v204, 13, v201
	v_lshl_add_u32 v204, v202, 7, v204
	v_and_b32_e32 v205, 1, v203
	v_lshl_add_u32 v204, v205, 3, v204
	v_lshrrev_b32_e32 v205, 1, v203
	v_and_b32_e32 v206, 7, v202
	v_xor_b32_e32 v205, v205, v206
	v_xor_b32_e32 v207, 0, v205
	v_lshl_add_u32 v180, v207, 4, v204
	v_xor_b32_e32 v207, 2, v205
	v_lshl_add_u32 v181, v207, 4, v204
	v_xor_b32_e32 v207, 4, v205
	v_lshl_add_u32 v182, v207, 4, v204
	v_xor_b32_e32 v207, 6, v205
	v_lshl_add_u32 v183, v207, 4, v204
	v_lshrrev_b32_e32 v206, 3, v200
	v_and_b32_e32 v207, 7, v200
	v_lshlrev_b32_e32 v184, 13, v201
	v_lshl_add_u32 v184, v206, 7, v184
	v_lshl_add_u32 v184, v207, 4, v184
	v_xor_b32_e32 v207, v207, v206
	v_lshlrev_b32_e32 v207, 4, v207
	v_mul_lo_u32 v185, v206, s17
	v_add_u32_e32 v185, v185, v207
	v_mov_b32_e32 v186, s17
	v_lshlrev_b32_e32 v186, 3, v186
	v_ashrrev_i32_e32 v64, 1, v104
	v_and_b32_e32 v64, 0xffffffc0, v64
	v_add_u32_e32 v64, s20, v64
	v_and_or_b32 v70, v104, 15, v64
	v_ashrrev_i32_e32 v71, 31, v70
	v_lshl_add_u64 v[74:75], v[70:71], 2, s[50:51]
	global_load_dword v64, v[74:75], off
	global_load_dword v174, v[74:75], off offset:64
	global_load_dword v175, v[74:75], off offset:128
	global_load_dword v176, v[74:75], off offset:192
	s_load_dword s96, s[68:69], 0x200
	s_load_dwordx2 s[100:101], s[68:69], 0xc0
	s_load_dwordx2 s[92:93], s[68:69], 0xc8
	s_load_dwordx2 s[94:95], s[68:69], 0x1c0
	v_lshrrev_b32_e32 v177, 6, v210
	v_and_b32_e32 v178, 63, v210
	v_lshlrev_b32_e32 v179, 6, v178
	v_lshlrev_b32_e32 v208, 4, v178
	v_add_u32_e32 v209, 0x1000000, v208
	v_readfirstlane_b32 s97, v177
	s_waitcnt lgkmcnt(0)
	s_cmp_lg_u32 s96, 0x200
	s_cbranch_scc1 .Lp9_conv_off
	s_lshl_b32 s96, s90, 2
	s_add_u32 s96, s96, s97
	s_lshr_b32 s97, s11, 6
	s_lshl_b32 s97, s97, 11
	s_add_u32 s96, s96, s97
	s_lshl_b32 s97, s96, 12
	s_add_u32 s100, s100, s97
	s_addc_u32 s101, s101, 0
	s_add_u32 s92, s92, s97
	s_addc_u32 s93, s93, 0
	global_load_dwordx4 v[110:113], v179, s[100:101]
	global_load_dwordx4 v[114:117], v179, s[100:101] offset:16
	global_load_dwordx4 v[118:121], v179, s[100:101] offset:32
	global_load_dwordx4 v[122:125], v179, s[100:101] offset:48
	global_load_dwordx4 v[126:129], v179, s[92:93]
	global_load_dwordx4 v[130:133], v179, s[92:93] offset:16
	global_load_dwordx4 v[134:137], v179, s[92:93] offset:32
	global_load_dwordx4 v[138:141], v179, s[92:93] offset:48
	s_lshl_b32 s97, s96, 10
	s_add_u32 s92, s94, s97
	s_addc_u32 s93, s95, 0
	s_lshl_b32 s97, s96, 2
	s_add_u32 s94, s94, s97
	s_addc_u32 s95, s95, 0
	s_add_u32 s94, s94, 0x2000000
	s_addc_u32 s95, s95, 0
	s_mov_b64 s[100:101], -1
	s_branch .Lp9_conv_on
.Lp9_conv_off:
	s_waitcnt vmcnt(0)
	s_mov_b64 s[100:101], 0
.Lp9_conv_on:
	v_lshrrev_b32_e32 v78, 2, v104
	v_and_b32_e32 v71, 64, v104
	v_mov_b32_e32 v76, v60
	v_mov_b32_e32 v60, v56
	v_mov_b32_e32 v56, v52
	v_mov_b32_e32 v52, v48
	v_and_b32_e32 v48, 12, v78
	v_or3_b32 v48, v71, v48, s19
	v_mov_b32_e32 v77, v62
	v_mov_b32_e32 v62, v61
	v_readlane_b32 s20, v248, 12
	v_mov_b32_e32 v61, v58
	v_mov_b32_e32 v58, v57
	v_mov_b32_e32 v57, v54
	v_mov_b32_e32 v54, v53
	v_mov_b32_e32 v53, v50
	v_mov_b32_e32 v50, v49
	v_readlane_b32 s22, v248, 14
	v_readlane_b32 s23, v248, 15
	v_ashrrev_i32_e32 v49, 31, v48
	v_lshlrev_b64 v[48:49], 1, v[48:49]
	v_mov_b64_e32 v[72:73], s[22:23]
	v_mad_i64_i32 v[78:79], s[8:9], v70, s17, v[72:73]
	v_lshl_add_u64 v[78:79], v[78:79], 0, v[48:49]
	s_add_i32 s11, s11, s14
	s_cmp_lt_i32 s11, s12
	v_readlane_b32 s21, v248, 13
	s_waitcnt vmcnt(8)
	v_fmamk_f32 v64, v64, 0x3a800000, v102
	v_mul_f32_e32 v71, 0x4b800000, v64
	v_cmp_gt_f32_e32 vcc, s16, v64
	s_nop 1
	v_cndmask_b32_e32 v64, v64, v71, vcc
	v_rsq_f32_e32 v64, v64
	s_nop 0
	v_mul_f32_e32 v71, 0x45800000, v64
	v_cndmask_b32_e32 v64, v64, v71, vcc
	v_pk_mul_f32 v[62:63], v[62:63], v[64:65] op_sel_hi:[1,0]
	v_pk_mul_f32 v[76:77], v[76:77], v[64:65] op_sel_hi:[1,0]
	v_pk_mul_f32 v[58:59], v[58:59], v[64:65] op_sel_hi:[1,0]
	v_pk_mul_f32 v[54:55], v[54:55], v[64:65] op_sel_hi:[1,0]
	v_pk_mul_f32 v[52:53], v[52:53], v[64:65] op_sel_hi:[1,0]
	v_pk_mul_f32 v[50:51], v[50:51], v[64:65] op_sel_hi:[1,0]
	v_and_b32_sdwa v80, v63, v103 dst_sel:DWORD dst_unused:UNUSED_PAD src0_sel:WORD_1 src1_sel:DWORD
	v_and_b32_sdwa v81, v62, v103 dst_sel:DWORD dst_unused:UNUSED_PAD src0_sel:WORD_1 src1_sel:DWORD
	v_pk_mul_f32 v[60:61], v[60:61], v[64:65] op_sel_hi:[1,0]
	v_pk_mul_f32 v[56:57], v[56:57], v[64:65] op_sel_hi:[1,0]
	v_and_b32_sdwa v64, v77, v103 dst_sel:DWORD dst_unused:UNUSED_PAD src0_sel:WORD_1 src1_sel:DWORD
	v_and_b32_sdwa v71, v76, v103 dst_sel:DWORD dst_unused:UNUSED_PAD src0_sel:WORD_1 src1_sel:DWORD
	v_and_b32_sdwa v84, v59, v103 dst_sel:DWORD dst_unused:UNUSED_PAD src0_sel:WORD_1 src1_sel:DWORD
	v_and_b32_sdwa v85, v58, v103 dst_sel:DWORD dst_unused:UNUSED_PAD src0_sel:WORD_1 src1_sel:DWORD
	v_and_b32_sdwa v88, v55, v103 dst_sel:DWORD dst_unused:UNUSED_PAD src0_sel:WORD_1 src1_sel:DWORD
	v_and_b32_sdwa v89, v54, v103 dst_sel:DWORD dst_unused:UNUSED_PAD src0_sel:WORD_1 src1_sel:DWORD
	v_and_b32_sdwa v90, v53, v103 dst_sel:DWORD dst_unused:UNUSED_PAD src0_sel:WORD_1 src1_sel:DWORD
	v_and_b32_sdwa v91, v52, v103 dst_sel:DWORD dst_unused:UNUSED_PAD src0_sel:WORD_1 src1_sel:DWORD
	v_and_b32_sdwa v92, v51, v103 dst_sel:DWORD dst_unused:UNUSED_PAD src0_sel:WORD_1 src1_sel:DWORD
	v_and_b32_sdwa v93, v50, v103 dst_sel:DWORD dst_unused:UNUSED_PAD src0_sel:WORD_1 src1_sel:DWORD
	v_add3_u32 v63, v63, v80, s18
	v_add3_u32 v62, v62, v81, s18
; DEVI unsigned pack2(float a, float b) { return (unsigned)f2bf(a) | ((unsigned)f2bf(b) << 16); }
; DEVI void phase_scaled(const Params& p, unsigned char* smem, const u16* A, const u16* Wt, int ntn, const float* ssq, u16* outp, int ldo) {
;     ...
;       const int m = m0 + wm * 64 + 16 * mi + col;
;       const float rstd = rsqrtf(ssq[m] * (1.f / D) + 1e-6f);
; #pragma unroll
;       for (int ni = 0; ni < 4; ++ni) {
;         const int n = n0 + wn * 64 + 16 * ni + 4 * quad;
;         const f32x4 v = acc[ni][mi];
;         uint2 pk; pk.x = pack2(v[0] * rstd, v[1] * rstd); pk.y = pack2(v[2] * rstd, v[3] * rstd);
;         *(uint2*)(outp + (size_t)m * ldo + n) = pk;
;       }
	v_and_b32_sdwa v82, v61, v103 dst_sel:DWORD dst_unused:UNUSED_PAD src0_sel:WORD_1 src1_sel:DWORD
	v_and_b32_sdwa v83, v60, v103 dst_sel:DWORD dst_unused:UNUSED_PAD src0_sel:WORD_1 src1_sel:DWORD
	v_and_b32_sdwa v86, v57, v103 dst_sel:DWORD dst_unused:UNUSED_PAD src0_sel:WORD_1 src1_sel:DWORD
	v_and_b32_sdwa v87, v56, v103 dst_sel:DWORD dst_unused:UNUSED_PAD src0_sel:WORD_1 src1_sel:DWORD
	v_add3_u32 v71, v76, v71, s18
	v_add3_u32 v64, v77, v64, s18
	v_add3_u32 v59, v59, v84, s18
	v_add3_u32 v58, v58, v85, s18
	v_add3_u32 v55, v55, v88, s18
	v_add3_u32 v54, v54, v89, s18
	v_add3_u32 v76, v52, v91, s18
	v_add3_u32 v77, v53, v90, s18
	v_add3_u32 v51, v51, v92, s18
	v_add3_u32 v50, v50, v93, s18
	v_and_b32_e32 v52, 0xffff0000, v63
	v_and_b32_e32 v53, 0xffff0000, v62
	v_add3_u32 v60, v60, v83, s18
	v_add3_u32 v61, v61, v82, s18
	v_add3_u32 v56, v56, v87, s18
	v_add3_u32 v57, v57, v86, s18
	v_and_b32_e32 v59, 0xffff0000, v59
	v_and_b32_e32 v58, 0xffff0000, v58
	v_and_b32_e32 v55, 0xffff0000, v55
	v_and_b32_e32 v54, 0xffff0000, v54
	v_and_b32_e32 v62, 0xffff0000, v51
	v_and_b32_e32 v63, 0xffff0000, v50
	v_or_b32_sdwa v51, v52, v64 dst_sel:DWORD dst_unused:UNUSED_PAD src0_sel:DWORD src1_sel:WORD_1
	v_or_b32_sdwa v50, v53, v71 dst_sel:DWORD dst_unused:UNUSED_PAD src0_sel:DWORD src1_sel:WORD_1
	v_or_b32_sdwa v53, v59, v61 dst_sel:DWORD dst_unused:UNUSED_PAD src0_sel:DWORD src1_sel:WORD_1
	v_or_b32_sdwa v52, v58, v60 dst_sel:DWORD dst_unused:UNUSED_PAD src0_sel:DWORD src1_sel:WORD_1
	v_or_b32_sdwa v55, v55, v57 dst_sel:DWORD dst_unused:UNUSED_PAD src0_sel:DWORD src1_sel:WORD_1
	v_or_b32_sdwa v54, v54, v56 dst_sel:DWORD dst_unused:UNUSED_PAD src0_sel:DWORD src1_sel:WORD_1
	v_or_b32_sdwa v57, v62, v77 dst_sel:DWORD dst_unused:UNUSED_PAD src0_sel:DWORD src1_sel:WORD_1
	v_or_b32_sdwa v56, v63, v76 dst_sel:DWORD dst_unused:UNUSED_PAD src0_sel:DWORD src1_sel:WORD_1
	v_readfirstlane_b32 s98, v78
	v_readfirstlane_b32 s99, v79
	ds_write_b64 v180, v[50:51]
	ds_write_b64 v181, v[52:53]
	ds_write_b64 v182, v[54:55]
	ds_write_b64 v183, v[56:57]
	v_mov_b32_e32 v52, v174
	v_mov_b32_e32 v51, v46
	v_mov_b32_e32 v46, v45
	v_mov_b32_e32 v45, v42
	v_mov_b32_e32 v42, v41
	v_mov_b32_e32 v41, v38
	v_mov_b32_e32 v38, v37
	v_mov_b32_e32 v37, v34
	v_mov_b32_e32 v34, v33
	v_mov_b32_e32 v50, v44
	v_mov_b32_e32 v44, v40
	v_mov_b32_e32 v40, v36
	v_mov_b32_e32 v36, v32
	v_or_b32_e32 v32, 16, v70
	s_nop 0
	v_fmamk_f32 v33, v52, 0x3a800000, v102
	v_mul_f32_e32 v52, 0x4b800000, v33
	v_cmp_gt_f32_e32 vcc, s16, v33
	s_nop 1
	v_cndmask_b32_e32 v33, v33, v52, vcc
	v_rsq_f32_e32 v52, v33
	v_mad_i64_i32 v[32:33], s[8:9], v32, s17, v[72:73]
	v_lshl_add_u64 v[32:33], v[32:33], 0, v[48:49]
	v_mul_f32_e32 v53, 0x45800000, v52
	v_cndmask_b32_e32 v52, v52, v53, vcc
	v_pk_mul_f32 v[46:47], v[46:47], v[52:53] op_sel_hi:[1,0]
	v_pk_mul_f32 v[50:51], v[50:51], v[52:53] op_sel_hi:[1,0]
	v_pk_mul_f32 v[42:43], v[42:43], v[52:53] op_sel_hi:[1,0]
	v_pk_mul_f32 v[38:39], v[38:39], v[52:53] op_sel_hi:[1,0]
	v_pk_mul_f32 v[36:37], v[36:37], v[52:53] op_sel_hi:[1,0]
	v_pk_mul_f32 v[34:35], v[34:35], v[52:53] op_sel_hi:[1,0]
	v_and_b32_sdwa v54, v47, v103 dst_sel:DWORD dst_unused:UNUSED_PAD src0_sel:WORD_1 src1_sel:DWORD
	v_and_b32_sdwa v55, v46, v103 dst_sel:DWORD dst_unused:UNUSED_PAD src0_sel:WORD_1 src1_sel:DWORD
	v_pk_mul_f32 v[44:45], v[44:45], v[52:53] op_sel_hi:[1,0]
	v_pk_mul_f32 v[40:41], v[40:41], v[52:53] op_sel_hi:[1,0]
	v_and_b32_sdwa v52, v51, v103 dst_sel:DWORD dst_unused:UNUSED_PAD src0_sel:WORD_1 src1_sel:DWORD
	v_and_b32_sdwa v53, v50, v103 dst_sel:DWORD dst_unused:UNUSED_PAD src0_sel:WORD_1 src1_sel:DWORD
	v_and_b32_sdwa v58, v43, v103 dst_sel:DWORD dst_unused:UNUSED_PAD src0_sel:WORD_1 src1_sel:DWORD
	v_and_b32_sdwa v59, v42, v103 dst_sel:DWORD dst_unused:UNUSED_PAD src0_sel:WORD_1 src1_sel:DWORD
	v_and_b32_sdwa v62, v39, v103 dst_sel:DWORD dst_unused:UNUSED_PAD src0_sel:WORD_1 src1_sel:DWORD
	v_and_b32_sdwa v63, v38, v103 dst_sel:DWORD dst_unused:UNUSED_PAD src0_sel:WORD_1 src1_sel:DWORD
	v_and_b32_sdwa v64, v37, v103 dst_sel:DWORD dst_unused:UNUSED_PAD src0_sel:WORD_1 src1_sel:DWORD
	v_and_b32_sdwa v71, v36, v103 dst_sel:DWORD dst_unused:UNUSED_PAD src0_sel:WORD_1 src1_sel:DWORD
	v_and_b32_sdwa v76, v35, v103 dst_sel:DWORD dst_unused:UNUSED_PAD src0_sel:WORD_1 src1_sel:DWORD
	v_and_b32_sdwa v77, v34, v103 dst_sel:DWORD dst_unused:UNUSED_PAD src0_sel:WORD_1 src1_sel:DWORD
	v_add3_u32 v47, v47, v54, s18
	v_add3_u32 v46, v46, v55, s18
	v_and_b32_sdwa v56, v45, v103 dst_sel:DWORD dst_unused:UNUSED_PAD src0_sel:WORD_1 src1_sel:DWORD
	v_and_b32_sdwa v57, v44, v103 dst_sel:DWORD dst_unused:UNUSED_PAD src0_sel:WORD_1 src1_sel:DWORD
	v_and_b32_sdwa v60, v41, v103 dst_sel:DWORD dst_unused:UNUSED_PAD src0_sel:WORD_1 src1_sel:DWORD
	v_and_b32_sdwa v61, v40, v103 dst_sel:DWORD dst_unused:UNUSED_PAD src0_sel:WORD_1 src1_sel:DWORD
	v_add3_u32 v50, v50, v53, s18
	v_add3_u32 v51, v51, v52, s18
	v_add3_u32 v43, v43, v58, s18
	v_add3_u32 v42, v42, v59, s18
	v_add3_u32 v39, v39, v62, s18
	v_add3_u32 v38, v38, v63, s18
	v_add3_u32 v52, v36, v71, s18
	v_add3_u32 v53, v37, v64, s18
	v_add3_u32 v35, v35, v76, s18
	v_add3_u32 v34, v34, v77, s18
	v_and_b32_e32 v36, 0xffff0000, v47
	v_and_b32_e32 v37, 0xffff0000, v46
	v_add3_u32 v44, v44, v57, s18
	v_add3_u32 v45, v45, v56, s18
	v_add3_u32 v40, v40, v61, s18
	v_add3_u32 v41, v41, v60, s18
	v_and_b32_e32 v43, 0xffff0000, v43
	v_and_b32_e32 v42, 0xffff0000, v42
	v_and_b32_e32 v39, 0xffff0000, v39
	v_and_b32_e32 v38, 0xffff0000, v38
	v_and_b32_e32 v46, 0xffff0000, v35
	v_and_b32_e32 v47, 0xffff0000, v34
	v_or_b32_sdwa v35, v36, v51 dst_sel:DWORD dst_unused:UNUSED_PAD src0_sel:DWORD src1_sel:WORD_1
; DEVI unsigned pack2(float a, float b) { return (unsigned)f2bf(a) | ((unsigned)f2bf(b) << 16); }
; DEVI void phase_scaled(const Params& p, unsigned char* smem, const u16* A, const u16* Wt, int ntn, const float* ssq, u16* outp, int ldo) {
;     ...
;       const int m = m0 + wm * 64 + 16 * mi + col;
;       const float rstd = rsqrtf(ssq[m] * (1.f / D) + 1e-6f);
; #pragma unroll
;       for (int ni = 0; ni < 4; ++ni) {
;         const int n = n0 + wn * 64 + 16 * ni + 4 * quad;
;         const f32x4 v = acc[ni][mi];
;         uint2 pk; pk.x = pack2(v[0] * rstd, v[1] * rstd); pk.y = pack2(v[2] * rstd, v[3] * rstd);
;         *(uint2*)(outp + (size_t)m * ldo + n) = pk;
;       }
	v_or_b32_sdwa v34, v37, v50 dst_sel:DWORD dst_unused:UNUSED_PAD src0_sel:DWORD src1_sel:WORD_1
	v_or_b32_sdwa v37, v43, v45 dst_sel:DWORD dst_unused:UNUSED_PAD src0_sel:DWORD src1_sel:WORD_1
	v_or_b32_sdwa v36, v42, v44 dst_sel:DWORD dst_unused:UNUSED_PAD src0_sel:DWORD src1_sel:WORD_1
	v_or_b32_sdwa v39, v39, v41 dst_sel:DWORD dst_unused:UNUSED_PAD src0_sel:DWORD src1_sel:WORD_1
	v_or_b32_sdwa v38, v38, v40 dst_sel:DWORD dst_unused:UNUSED_PAD src0_sel:DWORD src1_sel:WORD_1
	v_or_b32_sdwa v41, v46, v53 dst_sel:DWORD dst_unused:UNUSED_PAD src0_sel:DWORD src1_sel:WORD_1
	v_or_b32_sdwa v40, v47, v52 dst_sel:DWORD dst_unused:UNUSED_PAD src0_sel:DWORD src1_sel:WORD_1
	ds_write_b64 v180, v[34:35] offset:2048
	ds_write_b64 v181, v[36:37] offset:2048
	ds_write_b64 v182, v[38:39] offset:2048
	ds_write_b64 v183, v[40:41] offset:2048
	v_mov_b32_e32 v34, v175
	v_mov_b32_e32 v33, v30
	v_mov_b32_e32 v30, v29
	v_mov_b32_e32 v29, v26
	v_mov_b32_e32 v26, v25
	v_mov_b32_e32 v25, v22
	v_mov_b32_e32 v22, v21
	v_mov_b32_e32 v21, v18
	v_mov_b32_e32 v18, v17
	v_mov_b32_e32 v32, v28
	v_mov_b32_e32 v28, v24
	v_mov_b32_e32 v24, v20
	v_mov_b32_e32 v20, v16
	v_or_b32_e32 v16, 32, v70
	s_nop 0
	v_fmamk_f32 v17, v34, 0x3a800000, v102
	v_mul_f32_e32 v34, 0x4b800000, v17
	v_cmp_gt_f32_e32 vcc, s16, v17
	s_nop 1
	v_cndmask_b32_e32 v17, v17, v34, vcc
	v_rsq_f32_e32 v34, v17
	v_mad_i64_i32 v[16:17], s[8:9], v16, s17, v[72:73]
	v_lshl_add_u64 v[16:17], v[16:17], 0, v[48:49]
	v_mul_f32_e32 v35, 0x45800000, v34
	v_cndmask_b32_e32 v34, v34, v35, vcc
	v_pk_mul_f32 v[30:31], v[30:31], v[34:35] op_sel_hi:[1,0]
	v_pk_mul_f32 v[32:33], v[32:33], v[34:35] op_sel_hi:[1,0]
	v_pk_mul_f32 v[26:27], v[26:27], v[34:35] op_sel_hi:[1,0]
	v_pk_mul_f32 v[22:23], v[22:23], v[34:35] op_sel_hi:[1,0]
	v_pk_mul_f32 v[20:21], v[20:21], v[34:35] op_sel_hi:[1,0]
	v_pk_mul_f32 v[18:19], v[18:19], v[34:35] op_sel_hi:[1,0]
	v_and_b32_sdwa v36, v31, v103 dst_sel:DWORD dst_unused:UNUSED_PAD src0_sel:WORD_1 src1_sel:DWORD
	v_and_b32_sdwa v37, v30, v103 dst_sel:DWORD dst_unused:UNUSED_PAD src0_sel:WORD_1 src1_sel:DWORD
	v_pk_mul_f32 v[28:29], v[28:29], v[34:35] op_sel_hi:[1,0]
	v_pk_mul_f32 v[24:25], v[24:25], v[34:35] op_sel_hi:[1,0]
	v_and_b32_sdwa v34, v33, v103 dst_sel:DWORD dst_unused:UNUSED_PAD src0_sel:WORD_1 src1_sel:DWORD
	v_and_b32_sdwa v35, v32, v103 dst_sel:DWORD dst_unused:UNUSED_PAD src0_sel:WORD_1 src1_sel:DWORD
	v_and_b32_sdwa v40, v27, v103 dst_sel:DWORD dst_unused:UNUSED_PAD src0_sel:WORD_1 src1_sel:DWORD
	v_and_b32_sdwa v41, v26, v103 dst_sel:DWORD dst_unused:UNUSED_PAD src0_sel:WORD_1 src1_sel:DWORD
	v_and_b32_sdwa v44, v23, v103 dst_sel:DWORD dst_unused:UNUSED_PAD src0_sel:WORD_1 src1_sel:DWORD
	v_and_b32_sdwa v45, v22, v103 dst_sel:DWORD dst_unused:UNUSED_PAD src0_sel:WORD_1 src1_sel:DWORD
	v_and_b32_sdwa v46, v21, v103 dst_sel:DWORD dst_unused:UNUSED_PAD src0_sel:WORD_1 src1_sel:DWORD
	v_and_b32_sdwa v47, v20, v103 dst_sel:DWORD dst_unused:UNUSED_PAD src0_sel:WORD_1 src1_sel:DWORD
	v_and_b32_sdwa v50, v19, v103 dst_sel:DWORD dst_unused:UNUSED_PAD src0_sel:WORD_1 src1_sel:DWORD
	v_and_b32_sdwa v51, v18, v103 dst_sel:DWORD dst_unused:UNUSED_PAD src0_sel:WORD_1 src1_sel:DWORD
	v_add3_u32 v31, v31, v36, s18
	v_add3_u32 v30, v30, v37, s18
	v_and_b32_sdwa v38, v29, v103 dst_sel:DWORD dst_unused:UNUSED_PAD src0_sel:WORD_1 src1_sel:DWORD
	v_and_b32_sdwa v39, v28, v103 dst_sel:DWORD dst_unused:UNUSED_PAD src0_sel:WORD_1 src1_sel:DWORD
	v_and_b32_sdwa v42, v25, v103 dst_sel:DWORD dst_unused:UNUSED_PAD src0_sel:WORD_1 src1_sel:DWORD
	v_and_b32_sdwa v43, v24, v103 dst_sel:DWORD dst_unused:UNUSED_PAD src0_sel:WORD_1 src1_sel:DWORD
	v_add3_u32 v32, v32, v35, s18
	v_add3_u32 v33, v33, v34, s18
	v_add3_u32 v27, v27, v40, s18
	v_add3_u32 v26, v26, v41, s18
	v_add3_u32 v23, v23, v44, s18
	v_add3_u32 v22, v22, v45, s18
	v_add3_u32 v34, v20, v47, s18
	v_add3_u32 v35, v21, v46, s18
	v_add3_u32 v19, v19, v50, s18
	v_add3_u32 v18, v18, v51, s18
	v_and_b32_e32 v20, 0xffff0000, v31
	v_and_b32_e32 v21, 0xffff0000, v30
	v_add3_u32 v28, v28, v39, s18
	v_add3_u32 v29, v29, v38, s18
	v_add3_u32 v24, v24, v43, s18
	v_add3_u32 v25, v25, v42, s18
	v_and_b32_e32 v27, 0xffff0000, v27
	v_and_b32_e32 v26, 0xffff0000, v26
	v_and_b32_e32 v23, 0xffff0000, v23
	v_and_b32_e32 v22, 0xffff0000, v22
	v_and_b32_e32 v30, 0xffff0000, v19
	v_and_b32_e32 v31, 0xffff0000, v18
	v_or_b32_sdwa v19, v20, v33 dst_sel:DWORD dst_unused:UNUSED_PAD src0_sel:DWORD src1_sel:WORD_1
	v_or_b32_sdwa v18, v21, v32 dst_sel:DWORD dst_unused:UNUSED_PAD src0_sel:DWORD src1_sel:WORD_1
	v_or_b32_sdwa v21, v27, v29 dst_sel:DWORD dst_unused:UNUSED_PAD src0_sel:DWORD src1_sel:WORD_1
	v_or_b32_sdwa v20, v26, v28 dst_sel:DWORD dst_unused:UNUSED_PAD src0_sel:DWORD src1_sel:WORD_1
	v_or_b32_sdwa v23, v23, v25 dst_sel:DWORD dst_unused:UNUSED_PAD src0_sel:DWORD src1_sel:WORD_1
	v_or_b32_sdwa v22, v22, v24 dst_sel:DWORD dst_unused:UNUSED_PAD src0_sel:DWORD src1_sel:WORD_1
	v_or_b32_sdwa v25, v30, v35 dst_sel:DWORD dst_unused:UNUSED_PAD src0_sel:DWORD src1_sel:WORD_1
	v_or_b32_sdwa v24, v31, v34 dst_sel:DWORD dst_unused:UNUSED_PAD src0_sel:DWORD src1_sel:WORD_1
	ds_write_b64 v180, v[18:19] offset:4096
	ds_write_b64 v181, v[20:21] offset:4096
	ds_write_b64 v182, v[22:23] offset:4096
	ds_write_b64 v183, v[24:25] offset:4096
	v_mov_b32_e32 v18, v176
	v_mov_b32_e32 v17, v14
	v_mov_b32_e32 v14, v13
	v_mov_b32_e32 v13, v10
	v_mov_b32_e32 v10, v9
	v_mov_b32_e32 v9, v6
	v_mov_b32_e32 v6, v5
	v_mov_b32_e32 v5, v2
	v_mov_b32_e32 v2, v1
	v_mov_b32_e32 v16, v12
	v_mov_b32_e32 v12, v8
	v_mov_b32_e32 v8, v4
	v_mov_b32_e32 v4, v0
	v_or_b32_e32 v0, 48, v70
	s_nop 0
; DEVI unsigned pack2(float a, float b) { return (unsigned)f2bf(a) | ((unsigned)f2bf(b) << 16); }
; DEVI void phase_scaled(const Params& p, unsigned char* smem, const u16* A, const u16* Wt, int ntn, const float* ssq, u16* outp, int ldo) {
;     ...
;       const int m = m0 + wm * 64 + 16 * mi + col;
;       const float rstd = rsqrtf(ssq[m] * (1.f / D) + 1e-6f);
; #pragma unroll
;       for (int ni = 0; ni < 4; ++ni) {
;         const int n = n0 + wn * 64 + 16 * ni + 4 * quad;
;         const f32x4 v = acc[ni][mi];
;         uint2 pk; pk.x = pack2(v[0] * rstd, v[1] * rstd); pk.y = pack2(v[2] * rstd, v[3] * rstd);
;         *(uint2*)(outp + (size_t)m * ldo + n) = pk;
;       }
	v_fmamk_f32 v1, v18, 0x3a800000, v102
	v_mul_f32_e32 v18, 0x4b800000, v1
	v_cmp_gt_f32_e32 vcc, s16, v1
	s_nop 1
	v_cndmask_b32_e32 v1, v1, v18, vcc
	v_rsq_f32_e32 v18, v1
	v_mad_i64_i32 v[0:1], s[8:9], v0, s17, v[72:73]
	v_lshl_add_u64 v[0:1], v[0:1], 0, v[48:49]
	v_mul_f32_e32 v19, 0x45800000, v18
	v_cndmask_b32_e32 v18, v18, v19, vcc
	v_pk_mul_f32 v[14:15], v[14:15], v[18:19] op_sel_hi:[1,0]
	v_pk_mul_f32 v[16:17], v[16:17], v[18:19] op_sel_hi:[1,0]
	v_pk_mul_f32 v[10:11], v[10:11], v[18:19] op_sel_hi:[1,0]
	v_pk_mul_f32 v[6:7], v[6:7], v[18:19] op_sel_hi:[1,0]
	v_pk_mul_f32 v[4:5], v[4:5], v[18:19] op_sel_hi:[1,0]
	v_pk_mul_f32 v[2:3], v[2:3], v[18:19] op_sel_hi:[1,0]
	v_and_b32_sdwa v20, v15, v103 dst_sel:DWORD dst_unused:UNUSED_PAD src0_sel:WORD_1 src1_sel:DWORD
	v_and_b32_sdwa v21, v14, v103 dst_sel:DWORD dst_unused:UNUSED_PAD src0_sel:WORD_1 src1_sel:DWORD
	v_pk_mul_f32 v[12:13], v[12:13], v[18:19] op_sel_hi:[1,0]
	v_pk_mul_f32 v[8:9], v[8:9], v[18:19] op_sel_hi:[1,0]
	v_and_b32_sdwa v18, v17, v103 dst_sel:DWORD dst_unused:UNUSED_PAD src0_sel:WORD_1 src1_sel:DWORD
	v_and_b32_sdwa v19, v16, v103 dst_sel:DWORD dst_unused:UNUSED_PAD src0_sel:WORD_1 src1_sel:DWORD
	v_and_b32_sdwa v24, v11, v103 dst_sel:DWORD dst_unused:UNUSED_PAD src0_sel:WORD_1 src1_sel:DWORD
	v_and_b32_sdwa v25, v10, v103 dst_sel:DWORD dst_unused:UNUSED_PAD src0_sel:WORD_1 src1_sel:DWORD
	v_and_b32_sdwa v28, v7, v103 dst_sel:DWORD dst_unused:UNUSED_PAD src0_sel:WORD_1 src1_sel:DWORD
	v_and_b32_sdwa v29, v6, v103 dst_sel:DWORD dst_unused:UNUSED_PAD src0_sel:WORD_1 src1_sel:DWORD
	v_and_b32_sdwa v30, v5, v103 dst_sel:DWORD dst_unused:UNUSED_PAD src0_sel:WORD_1 src1_sel:DWORD
	v_and_b32_sdwa v31, v4, v103 dst_sel:DWORD dst_unused:UNUSED_PAD src0_sel:WORD_1 src1_sel:DWORD
	v_and_b32_sdwa v32, v3, v103 dst_sel:DWORD dst_unused:UNUSED_PAD src0_sel:WORD_1 src1_sel:DWORD
	v_and_b32_sdwa v33, v2, v103 dst_sel:DWORD dst_unused:UNUSED_PAD src0_sel:WORD_1 src1_sel:DWORD
	v_add3_u32 v15, v15, v20, s18
	v_add3_u32 v14, v14, v21, s18
	v_and_b32_sdwa v22, v13, v103 dst_sel:DWORD dst_unused:UNUSED_PAD src0_sel:WORD_1 src1_sel:DWORD
	v_and_b32_sdwa v23, v12, v103 dst_sel:DWORD dst_unused:UNUSED_PAD src0_sel:WORD_1 src1_sel:DWORD
	v_and_b32_sdwa v26, v9, v103 dst_sel:DWORD dst_unused:UNUSED_PAD src0_sel:WORD_1 src1_sel:DWORD
	v_and_b32_sdwa v27, v8, v103 dst_sel:DWORD dst_unused:UNUSED_PAD src0_sel:WORD_1 src1_sel:DWORD
	v_add3_u32 v16, v16, v19, s18
	v_add3_u32 v17, v17, v18, s18
	v_add3_u32 v11, v11, v24, s18
	v_add3_u32 v10, v10, v25, s18
	v_add3_u32 v7, v7, v28, s18
	v_add3_u32 v6, v6, v29, s18
	v_add3_u32 v18, v4, v31, s18
	v_add3_u32 v19, v5, v30, s18
	v_add3_u32 v3, v3, v32, s18
	v_add3_u32 v2, v2, v33, s18
	v_and_b32_e32 v4, 0xffff0000, v15
	v_and_b32_e32 v5, 0xffff0000, v14
	v_add3_u32 v12, v12, v23, s18
	v_add3_u32 v13, v13, v22, s18
	v_add3_u32 v8, v8, v27, s18
	v_add3_u32 v9, v9, v26, s18
	v_and_b32_e32 v11, 0xffff0000, v11
	v_and_b32_e32 v10, 0xffff0000, v10
	v_and_b32_e32 v7, 0xffff0000, v7
	v_and_b32_e32 v6, 0xffff0000, v6
	v_and_b32_e32 v14, 0xffff0000, v3
	v_and_b32_e32 v15, 0xffff0000, v2
	v_or_b32_sdwa v3, v4, v17 dst_sel:DWORD dst_unused:UNUSED_PAD src0_sel:DWORD src1_sel:WORD_1
	v_or_b32_sdwa v2, v5, v16 dst_sel:DWORD dst_unused:UNUSED_PAD src0_sel:DWORD src1_sel:WORD_1
	v_or_b32_sdwa v5, v11, v13 dst_sel:DWORD dst_unused:UNUSED_PAD src0_sel:DWORD src1_sel:WORD_1
	v_or_b32_sdwa v4, v10, v12 dst_sel:DWORD dst_unused:UNUSED_PAD src0_sel:DWORD src1_sel:WORD_1
	v_or_b32_sdwa v7, v7, v9 dst_sel:DWORD dst_unused:UNUSED_PAD src0_sel:DWORD src1_sel:WORD_1
	v_or_b32_sdwa v6, v6, v8 dst_sel:DWORD dst_unused:UNUSED_PAD src0_sel:DWORD src1_sel:WORD_1
	v_or_b32_sdwa v9, v14, v19 dst_sel:DWORD dst_unused:UNUSED_PAD src0_sel:DWORD src1_sel:WORD_1
	v_or_b32_sdwa v8, v15, v18 dst_sel:DWORD dst_unused:UNUSED_PAD src0_sel:DWORD src1_sel:WORD_1
	ds_write_b64 v180, v[2:3] offset:6144
	ds_write_b64 v181, v[4:5] offset:6144
	ds_write_b64 v182, v[6:7] offset:6144
	ds_write_b64 v183, v[8:9] offset:6144
	s_waitcnt lgkmcnt(0)
	ds_read_b128 v[212:215], v184 offset:0
	ds_read_b128 v[216:219], v184 offset:1024
	ds_read_b128 v[220:223], v184 offset:2048
	ds_read_b128 v[224:227], v184 offset:3072
	ds_read_b128 v[228:231], v184 offset:4096
	ds_read_b128 v[232:235], v184 offset:5120
	ds_read_b128 v[236:239], v184 offset:6144
	ds_read_b128 v[240:243], v184 offset:7168
	s_waitcnt lgkmcnt(7)
	global_store_dwordx4 v185, v[212:215], s[98:99]
	v_add_u32_e32 v185, v185, v186
	s_waitcnt lgkmcnt(6)
	global_store_dwordx4 v185, v[216:219], s[98:99]
	v_add_u32_e32 v185, v185, v186
	s_waitcnt lgkmcnt(5)
	global_store_dwordx4 v185, v[220:223], s[98:99]
	v_add_u32_e32 v185, v185, v186
	s_waitcnt lgkmcnt(4)
	global_store_dwordx4 v185, v[224:227], s[98:99]
	v_add_u32_e32 v185, v185, v186
	s_waitcnt lgkmcnt(3)
	global_store_dwordx4 v185, v[228:231], s[98:99]
	v_add_u32_e32 v185, v185, v186
	s_waitcnt lgkmcnt(2)
	global_store_dwordx4 v185, v[232:235], s[98:99]
	v_add_u32_e32 v185, v185, v186
	s_waitcnt lgkmcnt(1)
	global_store_dwordx4 v185, v[236:239], s[98:99]
	v_add_u32_e32 v185, v185, v186
	s_waitcnt lgkmcnt(0)
	global_store_dwordx4 v185, v[240:243], s[98:99]
	s_mov_b64 exec, s[100:101]
	s_mov_b32 s91, 0x43600000
	s_waitcnt vmcnt(8)
; DEVI void conv_fp8_rows(const float* __restrict__ src, unsigned char* __restrict__ dst, float* __restrict__ inv_scale,
;                         int rows, int gw, int nw, int lane) {
;     ...
;     float mx[2];
; #pragma unroll
;     for (int q = 0; q < 2; ++q) {
;       float m = 0.f;
; #pragma unroll
;       for (int i = 0; i < 4; ++i)
;         m = fmaxf(m, fmaxf(fmaxf(fabsf(v[q][i].x), fabsf(v[q][i].y)), fmaxf(fabsf(v[q][i].z), fabsf(v[q][i].w))));
;       mx[q] = m;
;     }
; #pragma unroll
;     for (int o = 32; o; o >>= 1) { mx[0] = fmaxf(mx[0], __shfl_xor(mx[0], o)); mx[1] = fmaxf(mx[1], __shfl_xor(mx[1], o)); }
; #pragma unroll
;     for (int q = 0; q < 2; ++q) {
;       if (q == 1 && !has1) break;
;       const int r = q ? r1 : r0;
;       const float sc = mx[q] > 0.f ? 224.f / mx[q] : 1.f;
;       if (lane == 0) inv_scale[r] = mx[q] > 0.f ? mx[q] * (1.f / 224.f) : 1.f;
;       uint4 o4;
;       o4.x = pk4_fp8(v[q][0].x * sc, v[q][0].y * sc, v[q][0].z * sc, v[q][0].w * sc);
;       o4.y = pk4_fp8(v[q][1].x * sc, v[q][1].y * sc, v[q][1].z * sc, v[q][1].w * sc);
;       o4.z = pk4_fp8(v[q][2].x * sc, v[q][2].y * sc, v[q][2].z * sc, v[q][2].w * sc);
;       o4.w = pk4_fp8(v[q][3].x * sc, v[q][3].y * sc, v[q][3].z * sc, v[q][3].w * sc);
;       ((uint4*)(dst + (size_t)r * 1024))[lane] = o4;
	v_max3_f32 v142, |v110|, |v111|, |v112|
	v_max3_f32 v142, v142, |v113|, |v114|
	v_max3_f32 v142, v142, |v115|, |v116|
	v_max3_f32 v142, v142, |v117|, |v118|
	v_max3_f32 v142, v142, |v119|, |v120|
	v_max3_f32 v142, v142, |v121|, |v122|
	v_max3_f32 v142, v142, |v123|, |v124|
	v_max_f32_e64 v142, v142, |v125|
	s_nop 1
	v_max_f32_dpp v142, v142, v142 row_ror:8 row_mask:0xf bank_mask:0xf
	s_nop 1
	v_max_f32_dpp v142, v142, v142 row_ror:4 row_mask:0xf bank_mask:0xf
	s_nop 1
	v_max_f32_dpp v142, v142, v142 row_ror:2 row_mask:0xf bank_mask:0xf
	s_nop 1
	v_max_f32_dpp v142, v142, v142 row_ror:1 row_mask:0xf bank_mask:0xf
	v_mov_b32_e32 v143, v142
	v_mov_b32_e32 v144, v142
	s_nop 1
	v_permlane16_swap_b32_e32 v143, v144
	s_nop 1
	v_max_f32_e32 v142, v143, v144
	v_mov_b32_e32 v143, v142
	v_mov_b32_e32 v144, v142
	s_nop 1
	v_permlane32_swap_b32_e32 v143, v144
	s_nop 1
	v_max_f32_e32 v142, v143, v144
	v_cmp_lt_f32_e64 s[96:97], 0, v142
	v_mul_f32_e32 v146, 0x3b924925, v142
	v_div_scale_f32 v150, vcc, v142, v142, s91
	v_rcp_f32_e32 v151, v150
	v_div_scale_f32 v152, vcc, s91, v142, s91
	v_fma_f32 v153, -v150, v151, 1.0
	v_fmac_f32_e32 v151, v153, v151
	v_mul_f32_e32 v153, v152, v151
	v_fma_f32 v154, -v150, v153, v152
	v_fmac_f32_e32 v153, v154, v151
	v_fma_f32 v150, -v150, v153, v152
	v_div_fmas_f32 v150, v150, v151, v153
	v_div_fixup_f32 v145, v150, v142, s91
	v_cndmask_b32_e64 v145, 1.0, v145, s[96:97]
	v_cndmask_b32_e64 v146, 1.0, v146, s[96:97]
	v_mul_f32_e32 v110, v110, v145
	v_mul_f32_e32 v111, v111, v145
	v_mul_f32_e32 v112, v112, v145
	v_mul_f32_e32 v113, v113, v145
	v_mul_f32_e32 v114, v114, v145
	v_mul_f32_e32 v115, v115, v145
	v_mul_f32_e32 v116, v116, v145
	v_mul_f32_e32 v117, v117, v145
	v_mul_f32_e32 v118, v118, v145
	v_mul_f32_e32 v119, v119, v145
	v_mul_f32_e32 v120, v120, v145
	v_mul_f32_e32 v121, v121, v145
	v_mul_f32_e32 v122, v122, v145
	v_mul_f32_e32 v123, v123, v145
	v_mul_f32_e32 v124, v124, v145
	v_mul_f32_e32 v125, v125, v145
	v_mov_b32_e32 v156, 0
	v_mov_b32_e32 v157, 0
	v_mov_b32_e32 v158, 0
	v_mov_b32_e32 v159, 0
	v_cvt_pk_fp8_f32 v156, v110, v111
	v_cvt_pk_fp8_f32 v156, v112, v113 op_sel:[0,0,1]
	v_cvt_pk_fp8_f32 v157, v114, v115
	v_cvt_pk_fp8_f32 v157, v116, v117 op_sel:[0,0,1]
	v_cvt_pk_fp8_f32 v158, v118, v119
	v_cvt_pk_fp8_f32 v158, v120, v121 op_sel:[0,0,1]
	v_cvt_pk_fp8_f32 v159, v122, v123
	v_cvt_pk_fp8_f32 v159, v124, v125 op_sel:[0,0,1]
	global_store_dwordx4 v208, v[156:159], s[92:93]
	v_max3_f32 v142, |v126|, |v127|, |v128|
	v_max3_f32 v142, v142, |v129|, |v130|
	v_max3_f32 v142, v142, |v131|, |v132|
	v_max3_f32 v142, v142, |v133|, |v134|
	v_max3_f32 v142, v142, |v135|, |v136|
	v_max3_f32 v142, v142, |v137|, |v138|
	v_max3_f32 v142, v142, |v139|, |v140|
	v_max_f32_e64 v142, v142, |v141|
	s_nop 1
	v_max_f32_dpp v142, v142, v142 row_ror:8 row_mask:0xf bank_mask:0xf
	s_nop 1
	v_max_f32_dpp v142, v142, v142 row_ror:4 row_mask:0xf bank_mask:0xf
	s_nop 1
	v_max_f32_dpp v142, v142, v142 row_ror:2 row_mask:0xf bank_mask:0xf
	s_nop 1
	v_max_f32_dpp v142, v142, v142 row_ror:1 row_mask:0xf bank_mask:0xf
	v_mov_b32_e32 v143, v142
	v_mov_b32_e32 v144, v142
	s_nop 1
	v_permlane16_swap_b32_e32 v143, v144
	s_nop 1
	v_max_f32_e32 v142, v143, v144
	v_mov_b32_e32 v143, v142
	v_mov_b32_e32 v144, v142
	s_nop 1
	v_permlane32_swap_b32_e32 v143, v144
	s_nop 1
	v_max_f32_e32 v142, v143, v144
	v_cmp_lt_f32_e64 s[96:97], 0, v142
	v_mul_f32_e32 v147, 0x3b924925, v142
	v_div_scale_f32 v150, vcc, v142, v142, s91
	v_rcp_f32_e32 v151, v150
	v_div_scale_f32 v152, vcc, s91, v142, s91
	v_fma_f32 v153, -v150, v151, 1.0
	v_fmac_f32_e32 v151, v153, v151
	v_mul_f32_e32 v153, v152, v151
	v_fma_f32 v154, -v150, v153, v152
	v_fmac_f32_e32 v153, v154, v151
	v_fma_f32 v150, -v150, v153, v152
	v_div_fmas_f32 v150, v150, v151, v153
	v_div_fixup_f32 v145, v150, v142, s91
	v_cndmask_b32_e64 v145, 1.0, v145, s[96:97]
	v_cndmask_b32_e64 v147, 1.0, v147, s[96:97]
	v_mul_f32_e32 v126, v126, v145
	v_mul_f32_e32 v127, v127, v145
	v_mul_f32_e32 v128, v128, v145
	v_mul_f32_e32 v129, v129, v145
	v_mul_f32_e32 v130, v130, v145
	v_mul_f32_e32 v131, v131, v145
	v_mul_f32_e32 v132, v132, v145
	v_mul_f32_e32 v133, v133, v145
	v_mul_f32_e32 v134, v134, v145
	v_mul_f32_e32 v135, v135, v145
	v_mul_f32_e32 v136, v136, v145
	v_mul_f32_e32 v137, v137, v145
	v_mul_f32_e32 v138, v138, v145
	v_mul_f32_e32 v139, v139, v145
	v_mul_f32_e32 v140, v140, v145
	v_mul_f32_e32 v141, v141, v145
	v_mov_b32_e32 v160, 0
	v_mov_b32_e32 v161, 0
	v_mov_b32_e32 v162, 0
	v_mov_b32_e32 v163, 0
	v_cvt_pk_fp8_f32 v160, v126, v127
	v_cvt_pk_fp8_f32 v160, v128, v129 op_sel:[0,0,1]
	v_cvt_pk_fp8_f32 v161, v130, v131
	v_cvt_pk_fp8_f32 v161, v132, v133 op_sel:[0,0,1]
	v_cvt_pk_fp8_f32 v162, v134, v135
	v_cvt_pk_fp8_f32 v162, v136, v137 op_sel:[0,0,1]
	v_cvt_pk_fp8_f32 v163, v138, v139
	v_cvt_pk_fp8_f32 v163, v140, v141 op_sel:[0,0,1]
	global_store_dwordx4 v209, v[160:163], s[92:93]
	v_mov_b32_e32 v148, 0
	v_mov_b32_e32 v149, 0x10000
	v_cmp_eq_u32_e64 s[96:97], 0, v178
	s_nop 3
	s_mov_b64 exec, s[96:97]
	global_store_dword v148, v146, s[94:95]
	global_store_dword v149, v147, s[94:95]
	s_mov_b64 exec, -1
	s_barrier
	s_cbranch_scc0 .LBB0_1163

; DEVI int launder(int x) { asm volatile("" : "+v"(x)); return x; }
; DEVI void phase_peer_route(const Params& p, unsigned char* smem) {
;     ...
;   {
;     const int t0_ = launder(threadIdx.x);
;     const int gw = (blockIdx.x * 256 + t0_) >> 6, nw = (gridDim.x * 256) >> 6;
;     conv_fp8_rows(p.peer_u, p.ub8, p.uscale, 16384, gw, nw, t0_ & 63);
;     conv_fp8_rows(p.peer_v, p.vb8, p.vscale, 16384, gw, nw, t0_ & 63);
;   }
.LBB0_1223:
	s_waitcnt lgkmcnt(0)
	s_cmp_lg_u32 s33, 0x200
	s_cbranch_scc1 .Lp10_conv_compiler
	s_mov_b64 s[10:11], 0
	s_branch .LBB0_1239

; template <bool COOP>
; __global__ void __launch_bounds__(256, 2) mega(Params p, int ph_lo, int ph_hi) {
	.amdhsa_kernel _Z4megaILb1EEv6Paramsii
		.amdhsa_group_segment_fixed_size 73744
		.amdhsa_private_segment_fixed_size 0
		.amdhsa_kernarg_size 768
		.amdhsa_user_sgpr_count 2
		.amdhsa_user_sgpr_dispatch_ptr 0
		.amdhsa_user_sgpr_queue_ptr 0
		.amdhsa_user_sgpr_kernarg_segment_ptr 1
		.amdhsa_user_sgpr_dispatch_id 0
		.amdhsa_user_sgpr_kernarg_preload_length 0
		.amdhsa_user_sgpr_kernarg_preload_offset 0
		.amdhsa_user_sgpr_private_segment_size 0
		.amdhsa_uses_dynamic_stack 0
		.amdhsa_enable_private_segment 0
		.amdhsa_system_sgpr_workgroup_id_x 1
		.amdhsa_system_sgpr_workgroup_id_y 0
		.amdhsa_system_sgpr_workgroup_id_z 0
		.amdhsa_system_sgpr_workgroup_info 0
		.amdhsa_system_vgpr_workitem_id 2
		.amdhsa_next_free_vgpr 249
		.amdhsa_next_free_sgpr 102
		.amdhsa_accum_offset 252
		.amdhsa_reserve_vcc 1
		.amdhsa_float_round_mode_32 0
		.amdhsa_float_round_mode_16_64 0
		.amdhsa_float_denorm_mode_32 3
		.amdhsa_float_denorm_mode_16_64 3
		.amdhsa_dx10_clamp 1
		.amdhsa_ieee_mode 1
		.amdhsa_fp16_overflow 0
		.amdhsa_tg_split 0
		.amdhsa_exception_fp_ieee_invalid_op 0
		.amdhsa_exception_fp_denorm_src 0
		.amdhsa_exception_fp_ieee_div_zero 0
		.amdhsa_exception_fp_ieee_overflow 0
		.amdhsa_exception_fp_ieee_underflow 0
		.amdhsa_exception_fp_ieee_inexact 0
		.amdhsa_exception_int_div_zero 0
	.end_amdhsa_kernel

; template <bool COOP>
; __global__ void __launch_bounds__(256, 2) mega(Params p, int ph_lo, int ph_hi) {
amdhsa.kernels:
  - .agpr_count:     0
    .args:
      - .offset:         0
        .size:           504
        .value_kind:     by_value
      - .offset:         504
        .size:           4
        .value_kind:     by_value
      - .offset:         508
        .size:           4
        .value_kind:     by_value
      - .offset:         512
        .size:           4
        .value_kind:     hidden_block_count_x
      - .offset:         516
        .size:           4
        .value_kind:     hidden_block_count_y
      - .offset:         520
        .size:           4
        .value_kind:     hidden_block_count_z
      - .offset:         524
        .size:           2
        .value_kind:     hidden_group_size_x
      - .offset:         526
        .size:           2
        .value_kind:     hidden_group_size_y
      - .offset:         528
        .size:           2
        .value_kind:     hidden_group_size_z
      - .offset:         530
        .size:           2
        .value_kind:     hidden_remainder_x
      - .offset:         532
        .size:           2
        .value_kind:     hidden_remainder_y
      - .offset:         534
        .size:           2
        .value_kind:     hidden_remainder_z
      - .offset:         552
        .size:           8
        .value_kind:     hidden_global_offset_x
      - .offset:         560
        .size:           8
        .value_kind:     hidden_global_offset_y
      - .offset:         568
        .size:           8
        .value_kind:     hidden_global_offset_z
      - .offset:         576
        .size:           2
        .value_kind:     hidden_grid_dims
      - .offset:         600
        .size:           8
        .value_kind:     hidden_multigrid_sync_arg
    .group_segment_fixed_size: 73744
    .kernarg_segment_align: 8
    .kernarg_segment_size: 768
    .language:       OpenCL C
    .language_version:
      - 2
      - 0
    .max_flat_workgroup_size: 256
    .name:           _Z4megaILb1EEv6Paramsii
    .private_segment_fixed_size: 0
    .sgpr_count:     108
    .sgpr_spill_count: 122
    .symbol:         _Z4megaILb1EEv6Paramsii.kd
    .uniform_work_group_size: 1
    .uses_dynamic_stack: false
    .vgpr_count:     249
    .vgpr_spill_count: 0
    .wavefront_size: 64
